# D4 top-k: first radix digit found by ballot counting from the smallest key's top byte (no LDS histogram atomics for pass 0; histogram kept as fallback)
# speedup vs baseline: 1.0104x; 1.0037x over previous
; __device__ __forceinline__ void dsa_index_phase(const Params& p, unsigned char* smem) {
;     ...
; #pragma unroll 1
;                 for (int pass = 0; pass < 4; ++pass) {
;                     const int shift = 24 - 8 * pass;
;                     const unsigned hmask = pass == 0 ? 0u : (0xFFFFFFFFu << (shift + 8));
;                     *(u32x4*)(H + lane * 4) = (u32x4){0u, 0u, 0u, 0u};
;                     asm volatile("s_waitcnt lgkmcnt(0)" ::: "memory");
; #pragma unroll
;                     for (int i = 0; i < 32; ++i) if (i < ni) { const unsigned uu = u[i]; if (uu != 0u && (uu & hmask) == prefix) atomicAdd(H + ((uu >> shift) & 255u), 1u); }
;                     asm volatile("s_waitcnt lgkmcnt(0)" ::: "memory");
;                     const u32x4 hv = *(const u32x4*)(H + lane * 4);
;                     const int tot = (int)(hv.x + hv.y + hv.z + hv.w);
;                     int rs = tot;
;                     rs += __builtin_amdgcn_update_dpp(0, rs, 0xB1, 0xF, 0xF, true);
;                     rs += __builtin_amdgcn_update_dpp(0, rs, 0x4E, 0xF, 0xF, true);
;                     rs += __builtin_amdgcn_update_dpp(0, rs, 0x141, 0xF, 0xF, true);
;                     rs += __builtin_amdgcn_update_dpp(0, rs, 0x140, 0xF, 0xF, true);
;                     int rowsel = 3, above = 0;
;                     {
;                         const int r3 = __builtin_amdgcn_readlane(rs, 48), r2 = __builtin_amdgcn_readlane(rs, 32), r1 = __builtin_amdgcn_readlane(rs, 16);
;                         if (need > r3) { above = r3; rowsel = 2; if (need > above + r2) { above += r2; rowsel = 1; if (need > above + r1) { above += r1; rowsel = 0; } } }
;                     }
;                     int lsel = rowsel * 16;
;                     for (int k = 15; k >= 0; --k) {
;                         const int cl = __builtin_amdgcn_readlane(tot, rowsel * 16 + k);
;                         if (need <= above + cl) { lsel = rowsel * 16 + k; break; }
;                         above += cl;
;                     }
;                     const int b3 = __builtin_amdgcn_readlane((int)hv.w, lsel), b2 = __builtin_amdgcn_readlane((int)hv.z, lsel), b1 = __builtin_amdgcn_readlane((int)hv.y, lsel);
;                     int bsel = 3;
;                     if (need > above + b3) { above += b3; bsel = 2; if (need > above + b2) { above += b2; bsel = 1; if (need > above + b1) { above += b1; bsel = 0; } } }
.Ltk_cv_end:
	v_mov_b32_e32 v123, v0
	v_min_u32_e32 v123, v123, v1
	v_min_u32_e32 v123, v123, v2
	v_min_u32_e32 v123, v123, v3
	s_cmp_le_u32 s9, 4
	s_cbranch_scc1 .Ltk_mn_end
	v_min_u32_e32 v123, v123, v4
	v_min_u32_e32 v123, v123, v5
	v_min_u32_e32 v123, v123, v6
	v_min_u32_e32 v123, v123, v7
	s_cmp_le_u32 s9, 8
	s_cbranch_scc1 .Ltk_mn_end
	v_min_u32_e32 v123, v123, v8
	v_min_u32_e32 v123, v123, v9
	v_min_u32_e32 v123, v123, v10
	v_min_u32_e32 v123, v123, v11
	s_cmp_le_u32 s9, 12
	s_cbranch_scc1 .Ltk_mn_end
	v_min_u32_e32 v123, v123, v12
	v_min_u32_e32 v123, v123, v13
	v_min_u32_e32 v123, v123, v14
	v_min_u32_e32 v123, v123, v15
	s_cmp_le_u32 s9, 16
	s_cbranch_scc1 .Ltk_mn_end
	v_min_u32_e32 v123, v123, v16
	v_min_u32_e32 v123, v123, v17
	v_min_u32_e32 v123, v123, v18
	v_min_u32_e32 v123, v123, v19
	s_cmp_le_u32 s9, 20
	s_cbranch_scc1 .Ltk_mn_end
	v_min_u32_e32 v123, v123, v20
	v_min_u32_e32 v123, v123, v21
	v_min_u32_e32 v123, v123, v22
	v_min_u32_e32 v123, v123, v23
	s_cmp_le_u32 s9, 24
	s_cbranch_scc1 .Ltk_mn_end
	v_min_u32_e32 v123, v123, v24
	v_min_u32_e32 v123, v123, v25
	v_min_u32_e32 v123, v123, v26
	v_min_u32_e32 v123, v123, v27
	s_cmp_le_u32 s9, 28
	s_cbranch_scc1 .Ltk_mn_end
	v_min_u32_e32 v123, v123, v28
	v_min_u32_e32 v123, v123, v29
	v_min_u32_e32 v123, v123, v30
	v_min_u32_e32 v123, v123, v31
.Ltk_mn_end:
	s_nop 1
	v_min_u32_dpp v123, v123, v123 row_shr:1 row_mask:0xf bank_mask:0xf
	s_nop 1
	v_min_u32_dpp v123, v123, v123 row_shr:2 row_mask:0xf bank_mask:0xf
	s_nop 1
	v_min_u32_dpp v123, v123, v123 row_shr:4 row_mask:0xf bank_mask:0xf
	s_nop 1
	v_min_u32_dpp v123, v123, v123 row_shr:8 row_mask:0xf bank_mask:0xf
	s_nop 1
	v_min_u32_dpp v123, v123, v123 row_bcast:15 row_mask:0xa bank_mask:0xf
	s_nop 1
	v_min_u32_dpp v123, v123, v123 row_bcast:31 row_mask:0xc bank_mask:0xf
	s_nop 1
	v_readlane_b32 s14, v123, 63
	s_mov_b32 s15, 0
	s_mov_b32 s17, 4
	s_lshr_b32 s14, s14, 24
.Ltk_b0:
	s_lshl_b32 s10, s14, 24
	s_or_b32 s10, s10, 0xffffff
	s_mov_b32 s16, 0
	v_cmp_ge_u32_e32 vcc, s10, v0
	s_bcnt1_i32_b64 s2, vcc
	s_add_u32 s16, s16, s2
	v_cmp_ge_u32_e32 vcc, s10, v1
	s_bcnt1_i32_b64 s2, vcc
	s_add_u32 s16, s16, s2
	v_cmp_ge_u32_e32 vcc, s10, v2
	s_bcnt1_i32_b64 s2, vcc
	s_add_u32 s16, s16, s2
	v_cmp_ge_u32_e32 vcc, s10, v3
	s_bcnt1_i32_b64 s2, vcc
	s_add_u32 s16, s16, s2
	s_cmp_le_u32 s9, 4
	s_cbranch_scc1 .Ltk_b0_cnt
	v_cmp_ge_u32_e32 vcc, s10, v4
	s_bcnt1_i32_b64 s2, vcc
	s_add_u32 s16, s16, s2
	v_cmp_ge_u32_e32 vcc, s10, v5
	s_bcnt1_i32_b64 s2, vcc
	s_add_u32 s16, s16, s2
	v_cmp_ge_u32_e32 vcc, s10, v6
	s_bcnt1_i32_b64 s2, vcc
	s_add_u32 s16, s16, s2
	v_cmp_ge_u32_e32 vcc, s10, v7
	s_bcnt1_i32_b64 s2, vcc
	s_add_u32 s16, s16, s2
	s_cmp_le_u32 s9, 8
	s_cbranch_scc1 .Ltk_b0_cnt
	v_cmp_ge_u32_e32 vcc, s10, v8
	s_bcnt1_i32_b64 s2, vcc
	s_add_u32 s16, s16, s2
	v_cmp_ge_u32_e32 vcc, s10, v9
	s_bcnt1_i32_b64 s2, vcc
	s_add_u32 s16, s16, s2
	v_cmp_ge_u32_e32 vcc, s10, v10
	s_bcnt1_i32_b64 s2, vcc
	s_add_u32 s16, s16, s2
	v_cmp_ge_u32_e32 vcc, s10, v11
	s_bcnt1_i32_b64 s2, vcc
	s_add_u32 s16, s16, s2
	s_cmp_le_u32 s9, 12
	s_cbranch_scc1 .Ltk_b0_cnt
	v_cmp_ge_u32_e32 vcc, s10, v12
	s_bcnt1_i32_b64 s2, vcc
	s_add_u32 s16, s16, s2
	v_cmp_ge_u32_e32 vcc, s10, v13
	s_bcnt1_i32_b64 s2, vcc
	s_add_u32 s16, s16, s2
	v_cmp_ge_u32_e32 vcc, s10, v14
	s_bcnt1_i32_b64 s2, vcc
	s_add_u32 s16, s16, s2
	v_cmp_ge_u32_e32 vcc, s10, v15
	s_bcnt1_i32_b64 s2, vcc
	s_add_u32 s16, s16, s2
	s_cmp_le_u32 s9, 16
	s_cbranch_scc1 .Ltk_b0_cnt
	v_cmp_ge_u32_e32 vcc, s10, v16
	s_bcnt1_i32_b64 s2, vcc
	s_add_u32 s16, s16, s2
	v_cmp_ge_u32_e32 vcc, s10, v17
	s_bcnt1_i32_b64 s2, vcc
	s_add_u32 s16, s16, s2
	v_cmp_ge_u32_e32 vcc, s10, v18
	s_bcnt1_i32_b64 s2, vcc
	s_add_u32 s16, s16, s2
	v_cmp_ge_u32_e32 vcc, s10, v19
	s_bcnt1_i32_b64 s2, vcc
	s_add_u32 s16, s16, s2
	s_cmp_le_u32 s9, 20
	s_cbranch_scc1 .Ltk_b0_cnt
	v_cmp_ge_u32_e32 vcc, s10, v20
	s_bcnt1_i32_b64 s2, vcc
	s_add_u32 s16, s16, s2
	v_cmp_ge_u32_e32 vcc, s10, v21
	s_bcnt1_i32_b64 s2, vcc
	s_add_u32 s16, s16, s2
	v_cmp_ge_u32_e32 vcc, s10, v22
	s_bcnt1_i32_b64 s2, vcc
	s_add_u32 s16, s16, s2
	v_cmp_ge_u32_e32 vcc, s10, v23
	s_bcnt1_i32_b64 s2, vcc
	s_add_u32 s16, s16, s2
	s_cmp_le_u32 s9, 24
	s_cbranch_scc1 .Ltk_b0_cnt
	v_cmp_ge_u32_e32 vcc, s10, v24
	s_bcnt1_i32_b64 s2, vcc
	s_add_u32 s16, s16, s2
	v_cmp_ge_u32_e32 vcc, s10, v25
	s_bcnt1_i32_b64 s2, vcc
	s_add_u32 s16, s16, s2
	v_cmp_ge_u32_e32 vcc, s10, v26
	s_bcnt1_i32_b64 s2, vcc
	s_add_u32 s16, s16, s2
	v_cmp_ge_u32_e32 vcc, s10, v27
	s_bcnt1_i32_b64 s2, vcc
	s_add_u32 s16, s16, s2
	s_cmp_le_u32 s9, 28
	s_cbranch_scc1 .Ltk_b0_cnt
	v_cmp_ge_u32_e32 vcc, s10, v28
	s_bcnt1_i32_b64 s2, vcc
	s_add_u32 s16, s16, s2
	v_cmp_ge_u32_e32 vcc, s10, v29
	s_bcnt1_i32_b64 s2, vcc
	s_add_u32 s16, s16, s2
	v_cmp_ge_u32_e32 vcc, s10, v30
	s_bcnt1_i32_b64 s2, vcc
	s_add_u32 s16, s16, s2
	v_cmp_ge_u32_e32 vcc, s10, v31
	s_bcnt1_i32_b64 s2, vcc
	s_add_u32 s16, s16, s2
.Ltk_b0_cnt:
	s_cmpk_ge_u32 s16, 0x100
	s_cbranch_scc1 .Ltk_b0_hit
	s_mov_b32 s15, s16
	s_add_u32 s14, s14, 1
	s_sub_u32 s17, s17, 1
	s_cmp_eq_u32 s17, 0
	s_cbranch_scc0 .Ltk_b0
	s_branch .Ltk_hist0
.Ltk_b0_hit:
	s_lshl_b32 s33, s14, 24
	s_movk_i32 s82, 0x100
	s_sub_u32 s82, s82, s15
	s_cmpk_eq_u32 s16, 0x100
	s_cbranch_scc1 .Ltk_b0_whole
	s_mov_b32 s11, 16
	s_branch .Ltk_pass
.Ltk_b0_whole:
	s_or_b32 s33, s33, 0xffffff
	s_branch .Ltk_compact
